# XCD-local row order in norm phases and prep_token (blocks with bid&7==x take batch x, the rows the neighbouring GEMM phases handle on the same blocks)
# speedup vs baseline: 1.0111x; 1.0013x over previous
; DI void prep_token(const Params& p, int l, int row, int lane) {
;     ...
;   const int l32 = lane & 31, c8 = l32 * 8, colA = 1152 + c8;
;   const u32x4 la_c = *(const u32x4*)(pa + colA), la_p = *(const u32x4*)(pa + opa + colA), la_n = *(const u32x4*)(pa + ona + colA);
;   const u32x4 lq0 = *(const u32x4*)(pbc + lane * 8), lq1 = *(const u32x4*)(pbc + 512 + c8), lkv = *(const u32x4*)(pbc + 768 + c8);
;   const u32x4 lrp = *(const u32x4*)(pbc + 1024 + (lane & 3) * 8);
;   const u32x4 lbg = *(const u32x4*)(pbc + 1056 + c8), lcc = *(const u32x4*)(pbc + 1312 + c8), lhh = *(const u32x4*)(pbc + 1568 + c8);
;   const u32x4 lcp = *(const u32x4*)(pbc + opb + 1312 + c8), lhp = *(const u32x4*)(pbc + opb + 1568 + c8);
;   const u32x4 lcn = *(const u32x4*)(pbc + onb + 1312 + c8), lhn = *(const u32x4*)(pbc + onb + 1568 + c8);
;   const float* mu = p.tshift_mu + (size_t)l * 2 * LDPA;
;   {
;     float c[8], pv[8], nx[8], o[8];
;     unpack8(la_c, c); unpack8(la_p, pv); unpack8(la_n, nx);
;     const f32x4 m0a = *(const f32x4*)(mu + colA), m0b = *(const f32x4*)(mu + colA + 4), m1a = *(const f32x4*)(mu + LDPA + colA), m1b = *(const f32x4*)(mu + LDPA + colA + 4);
; #pragma unroll
;     for (int j = 0; j < 8; ++j) {
;       const float m0 = j < 4 ? m0a[j & 3] : m0b[j & 3], m1 = j < 4 ? m1a[j & 3] : m1b[j & 3];
;       float t = c[j] + m0 * (pv[j] * mp - c[j]) + m1 * (nx[j] * mn - c[j]);
;       if (l32 < 8) { float e = __expf(2.f * t); t = 1.f - 2.f * __builtin_amdgcn_rcpf(1.f + e); }
;       else if (l32 >= 16) t = __builtin_amdgcn_rcpf(1.f + __expf(-t));
;       o[j] = t;
;     }
;     u32x4 w = {pk_bf16(o[0], o[1]), pk_bf16(o[2], o[3]), pk_bf16(o[4], o[5]), pk_bf16(o[6], o[7])};
;     if (lane < 8) *(u32x4*)(p.TW + (size_t)row * 64 + lane * 8) = w;
;     else if (lane < 16) *(u32x4*)(p.TA + (size_t)row * 64 + (lane - 8) * 8) = w;
;     else if (lane < 32) *(u32x4*)(p.TG + (size_t)row * 128 + (lane - 16) * 8) = w;
;   }
;   float f[8], ss = 0.f, s2 = 0.f, s3 = 0.f, fr_[8];
;   unpack8(lq0, f);
; #pragma unroll
;   for (int j = 0; j < 8; ++j) ss += f[j] * f[j];
;   unpack8(lq1, f);
;   if (lane < 32) {
; #pragma unroll
;     for (int j = 0; j < 8; ++j) ss += f[j] * f[j];
;   }
;   unpack8(lkv, f);
;   if (lane < 32) {
; #pragma unroll
;     for (int j = 0; j < 8; ++j) s2 += f[j] * f[j];
;   }
;   unpack8(lrp, fr_);
;   if (lane < 4) {
; #pragma unroll
.LBB0_442:
	v_readlane_b32 s0, v250, 7
	s_mov_b32 s88, s0
	s_lshl_b32 s2, s0, 5
	v_readlane_b32 s0, v253, 0
	v_readlane_b32 s1, v253, 1
	s_mov_b32 s94, s82
	s_mov_b32 s29, 0x38e38e39
	s_andn2_b64 vcc, exec, s[0:1]
	s_ashr_i32 s3, s2, 31
	s_cbranch_vccnz .LBB0_509
	v_lshlrev_b32_e32 v1, 3, v115
	v_and_b32_e32 v5, 64, v147
	v_and_b32_e32 v4, 24, v1
	v_xor_b32_e32 v1, 1, v147
	v_add_u32_e32 v5, 64, v5
	v_cmp_lt_i32_e64 s[0:1], v1, v5
	v_xor_b32_e32 v6, 2, v147
	v_readlane_b32 s72, v252, 24
	v_and_b32_e32 v3, 31, v114
	s_mul_i32 s21, s88, 0x2c00
	v_cndmask_b32_e64 v1, v147, v1, s[0:1]
	v_cmp_lt_i32_e64 s[0:1], v6, v5
	v_readlane_b32 s74, v252, 26
	s_mul_hi_i32 s20, s88, 0x2c00
	v_cndmask_b32_e64 v5, v147, v6, s[0:1]
	v_readlane_b32 s75, v252, 27
	s_add_u32 s0, s74, s21
	v_lshlrev_b32_e32 v6, 5, v3
	v_readlane_b32 s73, v252, 25
	v_readlane_b32 s76, v252, 28
	v_readlane_b32 s77, v252, 29
	v_readlane_b32 s78, v252, 30
	v_readlane_b32 s79, v252, 31
	v_readlane_b32 s80, v252, 32
	v_readlane_b32 s81, v252, 33
	v_readlane_b32 s82, v252, 34
	v_readlane_b32 s83, v252, 35
	v_readlane_b32 s84, v252, 36
	v_readlane_b32 s85, v252, 37
	v_readlane_b32 s86, v252, 38
	v_readlane_b32 s87, v252, 39
	s_addc_u32 s1, s75, s20
	v_add_u32_e32 v110, 0x1200, v6
	s_waitcnt vmcnt(4)
	v_lshl_add_u64 v[62:63], s[0:1], 0, v[110:111]
	s_mov_b64 s[0:1], 0x1600
	v_readlane_b32 s72, v251, 51
	v_lshl_add_u64 v[64:65], v[62:63], 0, s[0:1]
	s_lshl_b64 s[0:1], s[2:3], 2
	v_readlane_b32 s78, v251, 57
	v_readlane_b32 s79, v251, 58
	s_add_u32 s0, s78, s0
	s_mul_i32 s27, s88, 0xc00
	v_readlane_b32 s80, v251, 59
	s_addc_u32 s1, s79, s1
	v_lshlrev_b32_e32 v8, 2, v4
	v_mov_b32_e32 v9, v111
	s_mul_hi_i32 s26, s88, 0xc00
	v_readlane_b32 s4, v253, 36
	v_readlane_b32 s81, v251, 60
	s_waitcnt vmcnt(2)
	v_lshl_add_u64 v[72:73], s[0:1], 0, v[8:9]
	s_add_u32 s0, s80, s27
	v_lshlrev_b32_e32 v87, 2, v5
	v_and_b32_e32 v5, 2, v114
	v_lshlrev_b32_e32 v110, 4, v115
	v_readlane_b32 s10, v253, 42
	v_readlane_b32 s11, v253, 43
	v_readlane_b32 s12, v253, 44
	v_readlane_b32 s13, v253, 45
	v_readlane_b32 s14, v253, 46
	v_readlane_b32 s15, v253, 47
	v_readlane_b32 s18, v253, 50
	v_readlane_b32 s19, v253, 51
	s_addc_u32 s1, s81, s26
	v_mov_b32_e32 v7, v111
	v_lshlrev_b32_e32 v2, 3, v3
	v_cmp_eq_u32_e64 s[46:47], 0, v5
	v_and_b32_e32 v5, 1, v114
	v_readlane_b32 s8, v253, 40
	v_readlane_b32 s9, v253, 41
	v_lshl_add_u64 v[66:67], s[14:15], 0, v[110:111]
	v_lshl_add_u64 v[68:69], s[12:13], 0, v[110:111]
	v_lshl_add_u64 v[70:71], s[10:11], 0, v[110:111]
	s_waitcnt vmcnt(1)
	v_lshl_add_u64 v[74:75], s[0:1], 0, v[6:7]
	v_lshl_add_u64 v[76:77], s[18:19], 0, v[110:111]
	v_lshlrev_b32_e32 v110, 4, v3
	v_readlane_b32 s0, v252, 9
	v_cmp_lt_u32_e32 vcc, 7, v3
	v_cmp_lt_u32_e64 s[36:37], 15, v3
	v_cmp_lt_u32_e64 s[38:39], 7, v115
	v_cmp_lt_u32_e64 s[40:41], 15, v115
	v_cmp_gt_u32_e64 s[42:43], 32, v115
	v_cmp_gt_u32_e64 s[44:45], 4, v115
	v_lshlrev_b32_e32 v1, 2, v1
	v_cmp_eq_u32_e64 s[48:49], 0, v5
	v_lshl_add_u64 v[78:79], s[8:9], 0, v[110:111]
	s_lshr_b32 s28, s0, 2
	s_and_b32 s28, s28, 7
	s_mulk_i32 s28, 0x900
	s_lshr_b32 s5, s0, 5
	s_lshl_b32 s5, s5, 2
	s_add_i32 s28, s28, s5
	v_add_u32_e32 v80, s28, v158
	v_lshlrev_b32_e32 v82, 1, v2
	v_lshlrev_b32_e32 v84, 1, v4
	v_readlane_b32 s28, v254, 48
	v_readlane_b32 s5, v253, 37
	v_readlane_b32 s6, v253, 38
	v_readlane_b32 s7, v253, 39
	v_readlane_b32 s16, v253, 48
	v_readlane_b32 s17, v253, 49
	v_readlane_b32 s73, v251, 52
	v_readlane_b32 s74, v251, 53
	v_readlane_b32 s75, v251, 54
	v_readlane_b32 s76, v251, 55
	v_readlane_b32 s77, v251, 56
	v_readlane_b32 s82, v251, 61
	v_readlane_b32 s83, v251, 62
	v_readlane_b32 s84, v251, 63
	v_readlane_b32 s85, v252, 0
	v_readlane_b32 s86, v252, 1
	v_readlane_b32 s87, v252, 2
	s_branch .LBB0_445
.LBB0_444:
	s_or_b64 exec, exec, s[0:1]
	s_add_i32 s28, s28, s52
	v_readlane_b32 s0, v252, 10
	s_cmpk_gt_i32 s28, 0x11ff
	s_nop 0
	v_add_u32_e32 v80, 0x100, v80
	s_cbranch_scc1 .LBB0_509
